# c16 + pass C (4a,4b): next-unit L2 touch prefetch removed (its miss sat in front of every counted wait of the unit)
# speedup vs baseline: 1.0083x; 1.0083x over previous
.LBB0_1225:
	s_or_b64 exec, exec, s[0:1]
	v_mov_b32_e32 v26, 0
	s_branch .LBB0_1227
